# v68 + P4b: first main-loop iteration of units 2-4 peeled without the two waits that would block on the previous epilogue's write-through store acks
# speedup vs baseline: 1.0036x; 1.0036x over previous
.LBB0_355:
	s_mov_b32 s92, 0
	v_mov_b32_e32 v8, v196
	v_cndmask_b32_e64 v0, 0, 1, s[88:89]
	v_cmp_ne_u32_e64 s[0:1], 1, v0
	s_andn2_b64 vcc, exec, s[88:89]
	v_readfirstlane_b32 s14, v8
	s_cbranch_vccnz .LBB0_361
	s_lshr_b32 s8, s3, 29
	s_add_i32 s10, s2, s8
	s_and_b32 s8, s10, -8
	s_sub_i32 s11, s2, s8
	s_cmp_gt_i32 s11, -1
	s_cbranch_scc0 .LBB0_358
	s_lshl_b32 s12, s11, 7
	s_cbranch_execz .LBB0_359
	s_branch .LBB0_360

.LBB0_373:
	s_ashr_i32 s23, s22, 31
	s_lshl_b64 s[14:15], s[22:23], 19
	s_add_u32 s64, s36, s14
	s_addc_u32 s65, s37, s15
	s_and_b64 s[14:15], s[8:9], exec
	s_cselect_b32 s11, s65, s69
	s_cselect_b32 s13, s64, s68
	s_ashr_i32 s21, s20, 31
	s_lshl_b64 s[14:15], s[20:21], 19
	s_add_u32 s66, s58, s14
	s_addc_u32 s67, s59, s15
	s_and_b64 s[14:15], s[8:9], exec
	s_cselect_b32 s21, s67, s71
	s_cselect_b32 s23, s66, s70
	s_add_u32 s68, s68, 0x40080
	s_addc_u32 s69, s69, 0
	s_add_u32 s14, s70, 0x100
	v_mov_b32_e32 v0, 0
	s_addc_u32 s15, s71, 0
	s_mov_b32 s56, -2
	v_mov_b32_e32 v1, v0
	v_mov_b32_e32 v2, v0
	v_mov_b32_e32 v3, v0
	v_mov_b32_e32 v4, v0
	v_mov_b32_e32 v5, v0
	v_mov_b32_e32 v6, v0
	v_mov_b32_e32 v7, v0
	v_mov_b32_e32 v16, v0
	v_mov_b32_e32 v17, v0
	v_mov_b32_e32 v18, v0
	v_mov_b32_e32 v19, v0
	v_mov_b32_e32 v20, v0
	v_mov_b32_e32 v21, v0
	v_mov_b32_e32 v22, v0
	v_mov_b32_e32 v23, v0
	v_mov_b32_e32 v48, v0
	v_mov_b32_e32 v49, v0
	v_mov_b32_e32 v50, v0
	v_mov_b32_e32 v51, v0
	v_mov_b32_e32 v52, v0
	v_mov_b32_e32 v53, v0
	v_mov_b32_e32 v54, v0
	v_mov_b32_e32 v55, v0
	v_mov_b32_e32 v64, v0
	v_mov_b32_e32 v65, v0
	v_mov_b32_e32 v66, v0
	v_mov_b32_e32 v67, v0
	v_mov_b32_e32 v68, v0
	v_mov_b32_e32 v69, v0
	v_mov_b32_e32 v70, v0
	v_mov_b32_e32 v71, v0
	v_mov_b32_e32 v8, v0
	v_mov_b32_e32 v9, v0
	v_mov_b32_e32 v10, v0
	v_mov_b32_e32 v11, v0
	v_mov_b32_e32 v12, v0
	v_mov_b32_e32 v13, v0
	v_mov_b32_e32 v14, v0
	v_mov_b32_e32 v15, v0
	v_mov_b32_e32 v24, v0
	v_mov_b32_e32 v25, v0
	v_mov_b32_e32 v26, v0
	v_mov_b32_e32 v27, v0
	v_mov_b32_e32 v28, v0
	v_mov_b32_e32 v29, v0
	v_mov_b32_e32 v30, v0
	v_mov_b32_e32 v31, v0
	v_mov_b32_e32 v56, v0
	v_mov_b32_e32 v57, v0
	v_mov_b32_e32 v58, v0
	v_mov_b32_e32 v59, v0
	v_mov_b32_e32 v60, v0
	v_mov_b32_e32 v61, v0
	v_mov_b32_e32 v62, v0
	v_mov_b32_e32 v63, v0
	v_mov_b32_e32 v72, v0
	v_mov_b32_e32 v73, v0
	v_mov_b32_e32 v74, v0
	v_mov_b32_e32 v75, v0
	v_mov_b32_e32 v76, v0
	v_mov_b32_e32 v77, v0
	v_mov_b32_e32 v78, v0
	v_mov_b32_e32 v79, v0
	v_mov_b32_e32 v80, v0
	v_mov_b32_e32 v81, v0
	v_mov_b32_e32 v82, v0
	v_mov_b32_e32 v83, v0
	v_mov_b32_e32 v84, v0
	v_mov_b32_e32 v85, v0
	v_mov_b32_e32 v86, v0
	v_mov_b32_e32 v87, v0
	v_mov_b32_e32 v96, v0
	v_mov_b32_e32 v97, v0
	v_mov_b32_e32 v98, v0
	v_mov_b32_e32 v99, v0
	v_mov_b32_e32 v100, v0
	v_mov_b32_e32 v101, v0
	v_mov_b32_e32 v102, v0
	v_mov_b32_e32 v103, v0
	v_mov_b32_e32 v112, v0
	v_mov_b32_e32 v113, v0
	v_mov_b32_e32 v114, v0
	v_mov_b32_e32 v115, v0
	v_mov_b32_e32 v116, v0
	v_mov_b32_e32 v117, v0
	v_mov_b32_e32 v118, v0
	v_mov_b32_e32 v119, v0
	v_mov_b32_e32 v128, v0
	v_mov_b32_e32 v129, v0
	v_mov_b32_e32 v130, v0
	v_mov_b32_e32 v131, v0
	v_mov_b32_e32 v132, v0
	v_mov_b32_e32 v133, v0
	v_mov_b32_e32 v134, v0
	v_mov_b32_e32 v135, v0
	v_mov_b32_e32 v88, v0
	v_mov_b32_e32 v89, v0
	v_mov_b32_e32 v90, v0
	v_mov_b32_e32 v91, v0
	v_mov_b32_e32 v92, v0
	v_mov_b32_e32 v93, v0
	v_mov_b32_e32 v94, v0
	v_mov_b32_e32 v95, v0
	v_mov_b32_e32 v104, v0
	v_mov_b32_e32 v105, v0
	v_mov_b32_e32 v106, v0
	v_mov_b32_e32 v107, v0
	v_mov_b32_e32 v108, v0
	v_mov_b32_e32 v109, v0
	v_mov_b32_e32 v110, v0
	v_mov_b32_e32 v111, v0
	v_mov_b32_e32 v120, v0
	v_mov_b32_e32 v121, v0
	v_mov_b32_e32 v122, v0
	v_mov_b32_e32 v123, v0
	v_mov_b32_e32 v124, v0
	v_mov_b32_e32 v125, v0
	v_mov_b32_e32 v126, v0
	v_mov_b32_e32 v127, v0
	v_mov_b32_e32 v136, v0
	v_mov_b32_e32 v137, v0
	v_mov_b32_e32 v138, v0
	v_mov_b32_e32 v139, v0
	v_mov_b32_e32 v140, v0
	v_mov_b32_e32 v141, v0
	v_mov_b32_e32 v142, v0
	v_mov_b32_e32 v143, v0
	s_cmp_eq_u32 s92, 0
	s_cbranch_scc1 .LBB0_374
	ds_read_b128 v[32:35], v208
	ds_read_b128 v[36:39], v208 offset:1024
	ds_read_b128 v[40:43], v208 offset:2048
	ds_read_b128 v[44:47], v208 offset:3072
	ds_read_b128 v[144:147], v209
	ds_read_b128 v[148:151], v209 offset:1024
	ds_read_b128 v[152:155], v209 offset:2048
	ds_read_b128 v[156:159], v209 offset:3072
	s_add_u32 s33, s68, 0xfffc0080
	s_addc_u32 s57, s69, -1
	s_cmp_eq_u32 s56, 12
	s_cselect_b32 s73, s11, s57
	s_cselect_b32 s72, s13, s33
	s_cselect_b32 s71, s21, s15
	s_cselect_b32 s70, s23, s14
	v_lshl_add_u64 v[194:195], s[68:69], 0, v[174:175]
	s_add_i32 m0, s77, 0xc000
	ds_read_b128 v[182:185], v210
	ds_read_b128 v[186:189], v210 offset:1024
	ds_read_b128 v[190:193], v210 offset:2048
	ds_read_b128 v[198:201], v210 offset:3072
	ds_read_b128 v[214:217], v210 offset:4096
	ds_read_b128 v[218:221], v210 offset:5120
	ds_read_b128 v[222:225], v210 offset:6144
	ds_read_b128 v[226:229], v210 offset:7168
	global_load_lds_dwordx4 v[194:195], off
	v_lshl_add_u64 v[194:195], s[68:69], 0, v[176:177]
	s_add_i32 m0, s77, 0xe000
	s_nop 0
	global_load_lds_dwordx4 v[194:195], off
	s_waitcnt lgkmcnt(0)
	s_barrier
	s_setprio 1
	s_waitcnt lgkmcnt(0)
	v_mfma_f32_16x16x32_bf16 v[140:143], v[32:35], v[182:185], v[140:143]
	v_mfma_f32_16x16x32_bf16 v[136:139], v[40:43], v[182:185], v[136:139]
	v_mfma_f32_16x16x32_bf16 v[124:127], v[32:35], v[190:193], v[124:127]
	v_mfma_f32_16x16x32_bf16 v[120:123], v[40:43], v[190:193], v[120:123]
	v_mfma_f32_16x16x32_bf16 v[108:111], v[32:35], v[214:217], v[108:111]
	v_mfma_f32_16x16x32_bf16 v[104:107], v[40:43], v[214:217], v[104:107]
	v_mfma_f32_16x16x32_bf16 v[92:95], v[32:35], v[222:225], v[92:95]
	v_mfma_f32_16x16x32_bf16 v[88:91], v[40:43], v[222:225], v[88:91]
	v_mfma_f32_16x16x32_bf16 v[140:143], v[36:39], v[186:189], v[140:143]
	v_mfma_f32_16x16x32_bf16 v[136:139], v[44:47], v[186:189], v[136:139]
	v_mfma_f32_16x16x32_bf16 v[124:127], v[36:39], v[198:201], v[124:127]
	v_mfma_f32_16x16x32_bf16 v[120:123], v[44:47], v[198:201], v[120:123]
	v_mfma_f32_16x16x32_bf16 v[108:111], v[36:39], v[218:221], v[108:111]
	v_mfma_f32_16x16x32_bf16 v[104:107], v[44:47], v[218:221], v[104:107]
	v_mfma_f32_16x16x32_bf16 v[92:95], v[36:39], v[226:229], v[92:95]
	v_mfma_f32_16x16x32_bf16 v[88:91], v[44:47], v[226:229], v[88:91]
	s_setprio 0
	s_setprio 1
	v_mfma_f32_16x16x32_bf16 v[132:135], v[144:147], v[182:185], v[132:135]
	v_mfma_f32_16x16x32_bf16 v[128:131], v[152:155], v[182:185], v[128:131]
	v_mfma_f32_16x16x32_bf16 v[116:119], v[144:147], v[190:193], v[116:119]
	v_mfma_f32_16x16x32_bf16 v[112:115], v[152:155], v[190:193], v[112:115]
	v_mfma_f32_16x16x32_bf16 v[100:103], v[144:147], v[214:217], v[100:103]
	v_mfma_f32_16x16x32_bf16 v[96:99], v[152:155], v[214:217], v[96:99]
	v_mfma_f32_16x16x32_bf16 v[84:87], v[144:147], v[222:225], v[84:87]
	v_mfma_f32_16x16x32_bf16 v[80:83], v[152:155], v[222:225], v[80:83]
	v_mfma_f32_16x16x32_bf16 v[132:135], v[148:151], v[186:189], v[132:135]
	v_mfma_f32_16x16x32_bf16 v[128:131], v[156:159], v[186:189], v[128:131]
	v_mfma_f32_16x16x32_bf16 v[116:119], v[148:151], v[198:201], v[116:119]
	v_mfma_f32_16x16x32_bf16 v[112:115], v[156:159], v[198:201], v[112:115]
	v_mfma_f32_16x16x32_bf16 v[100:103], v[148:151], v[218:221], v[100:103]
	v_mfma_f32_16x16x32_bf16 v[96:99], v[156:159], v[218:221], v[96:99]
	v_mfma_f32_16x16x32_bf16 v[84:87], v[148:151], v[226:229], v[84:87]
	v_mfma_f32_16x16x32_bf16 v[80:83], v[156:159], v[226:229], v[80:83]
	s_setprio 0
	s_barrier
	s_add_i32 s33, s87, s76
	v_lshl_add_u64 v[194:195], s[70:71], 0, v[162:163]
	s_mov_b32 m0, s33
	ds_read_b128 v[182:185], v210 offset:16384
	ds_read_b128 v[186:189], v210 offset:17408
	ds_read_b128 v[190:193], v210 offset:18432
	ds_read_b128 v[198:201], v210 offset:19456
	ds_read_b128 v[214:217], v210 offset:20480
	ds_read_b128 v[218:221], v210 offset:21504
	ds_read_b128 v[222:225], v210 offset:22528
	ds_read_b128 v[226:229], v210 offset:23552
	global_load_lds_dwordx4 v[194:195], off
	s_add_i32 m0, s33, 0x2000
	s_add_u32 s88, s70, 0x40000
	v_lshl_add_u64 v[230:231], s[70:71], 0, v[166:167]
	s_addc_u32 s89, s71, 0
	s_add_i32 s33, s91, s76
	global_load_lds_dwordx4 v[230:231], off
	v_lshl_add_u64 v[232:233], s[88:89], 0, v[162:163]
	s_mov_b32 m0, s33
	v_lshl_add_u64 v[234:235], s[72:73], 0, v[164:165]
	global_load_lds_dwordx4 v[232:233], off
	v_lshl_add_u64 v[232:233], s[88:89], 0, v[166:167]
	s_add_i32 m0, s33, 0x2000
	s_nop 0
	global_load_lds_dwordx4 v[232:233], off
	v_lshl_add_u64 v[232:233], s[72:73], 0, v[160:161]
	s_mov_b32 m0, s77
	s_nop 0
	global_load_lds_dwordx4 v[232:233], off
	s_mov_b32 m0, s78
	s_nop 0
	global_load_lds_dwordx4 v[234:235], off
	s_waitcnt lgkmcnt(0)
	s_barrier
	s_setprio 1
	s_waitcnt lgkmcnt(0)
	v_mfma_f32_16x16x32_bf16 v[76:79], v[32:35], v[182:185], v[76:79]
	v_mfma_f32_16x16x32_bf16 v[72:75], v[40:43], v[182:185], v[72:75]
	v_mfma_f32_16x16x32_bf16 v[60:63], v[32:35], v[190:193], v[60:63]
	v_mfma_f32_16x16x32_bf16 v[56:59], v[40:43], v[190:193], v[56:59]
	v_mfma_f32_16x16x32_bf16 v[28:31], v[32:35], v[214:217], v[28:31]
	v_mfma_f32_16x16x32_bf16 v[24:27], v[40:43], v[214:217], v[24:27]
	v_mfma_f32_16x16x32_bf16 v[12:15], v[32:35], v[222:225], v[12:15]
	v_mfma_f32_16x16x32_bf16 v[8:11], v[40:43], v[222:225], v[8:11]
	v_mfma_f32_16x16x32_bf16 v[76:79], v[36:39], v[186:189], v[76:79]
	v_mfma_f32_16x16x32_bf16 v[72:75], v[44:47], v[186:189], v[72:75]
	v_mfma_f32_16x16x32_bf16 v[60:63], v[36:39], v[198:201], v[60:63]
	v_mfma_f32_16x16x32_bf16 v[56:59], v[44:47], v[198:201], v[56:59]
	v_mfma_f32_16x16x32_bf16 v[28:31], v[36:39], v[218:221], v[28:31]
	v_mfma_f32_16x16x32_bf16 v[24:27], v[44:47], v[218:221], v[24:27]
	v_mfma_f32_16x16x32_bf16 v[12:15], v[36:39], v[226:229], v[12:15]
	v_mfma_f32_16x16x32_bf16 v[8:11], v[44:47], v[226:229], v[8:11]
	s_setprio 0
	s_setprio 1
	v_mfma_f32_16x16x32_bf16 v[20:23], v[144:147], v[214:217], v[20:23]
	v_mfma_f32_16x16x32_bf16 v[16:19], v[152:155], v[214:217], v[16:19]
	v_mfma_f32_16x16x32_bf16 v[4:7], v[144:147], v[222:225], v[4:7]
	v_mfma_f32_16x16x32_bf16 v[0:3], v[152:155], v[222:225], v[0:3]
	v_mfma_f32_16x16x32_bf16 v[32:35], v[144:147], v[182:185], v[68:71]
	v_mfma_f32_16x16x32_bf16 v[36:39], v[152:155], v[182:185], v[64:67]
	v_mfma_f32_16x16x32_bf16 v[40:43], v[144:147], v[190:193], v[52:55]
	v_mfma_f32_16x16x32_bf16 v[44:47], v[152:155], v[190:193], v[48:51]
	v_mfma_f32_16x16x32_bf16 v[20:23], v[148:151], v[218:221], v[20:23]
	v_mfma_f32_16x16x32_bf16 v[16:19], v[156:159], v[218:221], v[16:19]
	v_mfma_f32_16x16x32_bf16 v[4:7], v[148:151], v[226:229], v[4:7]
	v_mfma_f32_16x16x32_bf16 v[0:3], v[156:159], v[226:229], v[0:3]
	v_mfma_f32_16x16x32_bf16 v[32:35], v[148:151], v[186:189], v[32:35]
	v_mfma_f32_16x16x32_bf16 v[36:39], v[156:159], v[186:189], v[36:39]
	v_mfma_f32_16x16x32_bf16 v[40:43], v[148:151], v[198:201], v[40:43]
	v_mfma_f32_16x16x32_bf16 v[44:47], v[156:159], v[198:201], v[44:47]
	s_setprio 0
	s_barrier
	s_add_i32 s33, 0, 0x18000
	s_add_i32 s57, 0, 0x1c000
	v_add_u32_e32 v68, s33, v207
	v_add_u32_e32 v156, s57, v207
	ds_read_b128 v[48:51], v68
	ds_read_b128 v[52:55], v68 offset:1024
	ds_read_b128 v[64:67], v68 offset:2048
	ds_read_b128 v[68:71], v68 offset:3072
	ds_read_b128 v[144:147], v156
	ds_read_b128 v[148:151], v156 offset:1024
	ds_read_b128 v[152:155], v156 offset:2048
	ds_read_b128 v[156:159], v156 offset:3072
	s_add_u32 s72, s72, 0x40000
	s_addc_u32 s73, s73, 0
	s_mov_b32 m0, s79
	v_lshl_add_u64 v[236:237], s[72:73], 0, v[160:161]
	ds_read_b128 v[182:185], v210 offset:32768
	ds_read_b128 v[186:189], v210 offset:33792
	ds_read_b128 v[190:193], v210 offset:34816
	ds_read_b128 v[198:201], v210 offset:35840
	ds_read_b128 v[214:217], v210 offset:36864
	ds_read_b128 v[218:221], v210 offset:37888
	ds_read_b128 v[222:225], v210 offset:38912
	ds_read_b128 v[226:229], v210 offset:39936
	global_load_lds_dwordx4 v[236:237], off
	v_lshl_add_u64 v[236:237], s[72:73], 0, v[164:165]
	s_mov_b32 m0, s82
	s_nop 0
	global_load_lds_dwordx4 v[236:237], off
	s_waitcnt vmcnt(8)
	s_waitcnt lgkmcnt(0)
	s_barrier
	s_setprio 1
	s_waitcnt lgkmcnt(0)
	v_mfma_f32_16x16x32_bf16 v[140:143], v[48:51], v[182:185], v[140:143]
	v_mfma_f32_16x16x32_bf16 v[136:139], v[64:67], v[182:185], v[136:139]
	v_mfma_f32_16x16x32_bf16 v[124:127], v[48:51], v[190:193], v[124:127]
	v_mfma_f32_16x16x32_bf16 v[120:123], v[64:67], v[190:193], v[120:123]
	v_mfma_f32_16x16x32_bf16 v[108:111], v[48:51], v[214:217], v[108:111]
	v_mfma_f32_16x16x32_bf16 v[104:107], v[64:67], v[214:217], v[104:107]
	v_mfma_f32_16x16x32_bf16 v[92:95], v[48:51], v[222:225], v[92:95]
	v_mfma_f32_16x16x32_bf16 v[88:91], v[64:67], v[222:225], v[88:91]
	v_mfma_f32_16x16x32_bf16 v[140:143], v[52:55], v[186:189], v[140:143]
	v_mfma_f32_16x16x32_bf16 v[136:139], v[68:71], v[186:189], v[136:139]
	v_mfma_f32_16x16x32_bf16 v[124:127], v[52:55], v[198:201], v[124:127]
	v_mfma_f32_16x16x32_bf16 v[120:123], v[68:71], v[198:201], v[120:123]
	v_mfma_f32_16x16x32_bf16 v[108:111], v[52:55], v[218:221], v[108:111]
	v_mfma_f32_16x16x32_bf16 v[104:107], v[68:71], v[218:221], v[104:107]
	v_mfma_f32_16x16x32_bf16 v[92:95], v[52:55], v[226:229], v[92:95]
	v_mfma_f32_16x16x32_bf16 v[88:91], v[68:71], v[226:229], v[88:91]
	s_setprio 0
	s_setprio 1
	v_mfma_f32_16x16x32_bf16 v[132:135], v[144:147], v[182:185], v[132:135]
	v_mfma_f32_16x16x32_bf16 v[128:131], v[152:155], v[182:185], v[128:131]
	v_mfma_f32_16x16x32_bf16 v[116:119], v[144:147], v[190:193], v[116:119]
	v_mfma_f32_16x16x32_bf16 v[112:115], v[152:155], v[190:193], v[112:115]
	v_mfma_f32_16x16x32_bf16 v[100:103], v[144:147], v[214:217], v[100:103]
	v_mfma_f32_16x16x32_bf16 v[96:99], v[152:155], v[214:217], v[96:99]
	v_mfma_f32_16x16x32_bf16 v[84:87], v[144:147], v[222:225], v[84:87]
	v_mfma_f32_16x16x32_bf16 v[80:83], v[152:155], v[222:225], v[80:83]
	v_mfma_f32_16x16x32_bf16 v[132:135], v[148:151], v[186:189], v[132:135]
	v_mfma_f32_16x16x32_bf16 v[128:131], v[156:159], v[186:189], v[128:131]
	v_mfma_f32_16x16x32_bf16 v[116:119], v[148:151], v[198:201], v[116:119]
	v_mfma_f32_16x16x32_bf16 v[112:115], v[156:159], v[198:201], v[112:115]
	v_mfma_f32_16x16x32_bf16 v[100:103], v[148:151], v[218:221], v[100:103]
	v_mfma_f32_16x16x32_bf16 v[96:99], v[156:159], v[218:221], v[96:99]
	v_mfma_f32_16x16x32_bf16 v[84:87], v[148:151], v[226:229], v[84:87]
	v_mfma_f32_16x16x32_bf16 v[80:83], v[156:159], v[226:229], v[80:83]
	s_setprio 0
	s_barrier
	s_add_i32 s33, s33, s76
	v_lshl_add_u64 v[194:195], v[194:195], 0, s[16:17]
	s_mov_b32 m0, s33
	ds_read_b128 v[182:185], v210 offset:49152
	ds_read_b128 v[186:189], v210 offset:50176
	ds_read_b128 v[190:193], v210 offset:51200
	ds_read_b128 v[198:201], v210 offset:52224
	ds_read_b128 v[214:217], v210 offset:53248
	ds_read_b128 v[218:221], v210 offset:54272
	ds_read_b128 v[222:225], v210 offset:55296
	ds_read_b128 v[226:229], v210 offset:56320
	global_load_lds_dwordx4 v[194:195], off
	s_add_i32 m0, s33, 0x2000
	s_add_u32 s70, s70, 0x40080
	v_lshl_add_u64 v[194:195], v[230:231], 0, s[16:17]
	s_addc_u32 s71, s71, 0
	s_add_i32 s33, s57, s76
	global_load_lds_dwordx4 v[194:195], off
	v_lshl_add_u64 v[194:195], s[70:71], 0, v[162:163]
	s_mov_b32 m0, s33
	s_nop 0
	global_load_lds_dwordx4 v[194:195], off
	v_lshl_add_u64 v[194:195], s[70:71], 0, v[166:167]
	s_add_i32 m0, s33, 0x2000
	s_nop 0
	global_load_lds_dwordx4 v[194:195], off
	v_lshl_add_u64 v[194:195], v[232:233], 0, s[16:17]
	s_mov_b32 m0, s85
	s_nop 0
	global_load_lds_dwordx4 v[194:195], off
	v_lshl_add_u64 v[194:195], v[234:235], 0, s[16:17]
	s_mov_b32 m0, s86
	s_nop 0
	global_load_lds_dwordx4 v[194:195], off
	s_waitcnt vmcnt(8)
	s_waitcnt lgkmcnt(0)
	s_barrier
	s_setprio 1
	s_waitcnt lgkmcnt(0)
	v_mfma_f32_16x16x32_bf16 v[76:79], v[48:51], v[182:185], v[76:79]
	v_mfma_f32_16x16x32_bf16 v[72:75], v[64:67], v[182:185], v[72:75]
	v_mfma_f32_16x16x32_bf16 v[60:63], v[48:51], v[190:193], v[60:63]
	v_mfma_f32_16x16x32_bf16 v[56:59], v[64:67], v[190:193], v[56:59]
	v_mfma_f32_16x16x32_bf16 v[28:31], v[48:51], v[214:217], v[28:31]
	v_mfma_f32_16x16x32_bf16 v[24:27], v[64:67], v[214:217], v[24:27]
	v_mfma_f32_16x16x32_bf16 v[12:15], v[48:51], v[222:225], v[12:15]
	v_mfma_f32_16x16x32_bf16 v[8:11], v[64:67], v[222:225], v[8:11]
	v_mfma_f32_16x16x32_bf16 v[76:79], v[52:55], v[186:189], v[76:79]
	v_mfma_f32_16x16x32_bf16 v[72:75], v[68:71], v[186:189], v[72:75]
	v_mfma_f32_16x16x32_bf16 v[60:63], v[52:55], v[198:201], v[60:63]
	v_mfma_f32_16x16x32_bf16 v[56:59], v[68:71], v[198:201], v[56:59]
	v_mfma_f32_16x16x32_bf16 v[28:31], v[52:55], v[218:221], v[28:31]
	v_mfma_f32_16x16x32_bf16 v[24:27], v[68:71], v[218:221], v[24:27]
	v_mfma_f32_16x16x32_bf16 v[12:15], v[52:55], v[226:229], v[12:15]
	v_mfma_f32_16x16x32_bf16 v[8:11], v[68:71], v[226:229], v[8:11]
	s_setprio 0
	s_setprio 1
	v_mfma_f32_16x16x32_bf16 v[32:35], v[144:147], v[182:185], v[32:35]
	v_mfma_f32_16x16x32_bf16 v[68:71], v[148:151], v[186:189], v[32:35]
	v_mfma_f32_16x16x32_bf16 v[32:35], v[152:155], v[182:185], v[36:39]
	v_mfma_f32_16x16x32_bf16 v[64:67], v[156:159], v[186:189], v[32:35]
	v_mfma_f32_16x16x32_bf16 v[32:35], v[144:147], v[190:193], v[40:43]
	v_mfma_f32_16x16x32_bf16 v[52:55], v[148:151], v[198:201], v[32:35]
	v_mfma_f32_16x16x32_bf16 v[32:35], v[152:155], v[190:193], v[44:47]
	v_mfma_f32_16x16x32_bf16 v[20:23], v[144:147], v[214:217], v[20:23]
	v_mfma_f32_16x16x32_bf16 v[16:19], v[152:155], v[214:217], v[16:19]
	v_mfma_f32_16x16x32_bf16 v[4:7], v[144:147], v[222:225], v[4:7]
	v_mfma_f32_16x16x32_bf16 v[0:3], v[152:155], v[222:225], v[0:3]
	v_mfma_f32_16x16x32_bf16 v[48:51], v[156:159], v[198:201], v[32:35]
	v_mfma_f32_16x16x32_bf16 v[20:23], v[148:151], v[218:221], v[20:23]
	v_mfma_f32_16x16x32_bf16 v[16:19], v[156:159], v[218:221], v[16:19]
	v_mfma_f32_16x16x32_bf16 v[4:7], v[148:151], v[226:229], v[4:7]
	v_mfma_f32_16x16x32_bf16 v[0:3], v[156:159], v[226:229], v[0:3]
	s_setprio 0
	s_barrier
	s_add_i32 s56, s56, 2
	s_add_u32 s68, s68, 0x100
	s_addc_u32 s69, s69, 0
	s_add_u32 s14, s14, 0x100
	s_addc_u32 s15, s15, 0
	s_cmp_gt_u32 s56, 13
	s_branch .LBB0_374

.LBB0_436:
	v_lshlrev_b64 v[0:1], 11, v[182:183]
	v_lshl_add_u64 v[4:5], v[186:187], 0, v[0:1]
	v_cvt_pk_bf16_f32 v0, v16, v17
	v_cvt_pk_bf16_f32 v1, v18, v19
	v_cvt_pk_bf16_f32 v2, v20, v21
	v_cvt_pk_bf16_f32 v3, v22, v23
	s_andn2_b64 vcc, exec, s[8:9]
	s_mov_b64 s[8:9], -1
	global_store_dwordx4 v[4:5], v[0:3], off sc1
	s_nop 1
	v_cvt_pk_bf16_f32 v0, v24, v25
	v_cvt_pk_bf16_f32 v1, v26, v27
	v_cvt_pk_bf16_f32 v2, v28, v29
	v_cvt_pk_bf16_f32 v3, v30, v31
	global_store_dwordx4 v[4:5], v[0:3], off offset:64 sc1
	s_mov_b32 s92, 1
	s_cbranch_vccnz .LBB0_366
	s_andn2_b64 vcc, exec, s[0:1]
	s_cbranch_vccnz .LBB0_365
	s_barrier
	s_branch .LBB0_365

.LBB0_440:
	s_nop 0
	s_cmpk_lt_i32 s2, 0x100
	s_cselect_b64 s[0:1], -1, 0
	s_xor_b64 s[8:9], s[62:63], -1
	s_and_b64 s[0:1], s[0:1], s[8:9]
	s_and_b64 vcc, exec, s[0:1]
	s_cbranch_vccz .LBB0_447
	v_lshlrev_b32_e32 v0, 3, v197
	v_readlane_b32 s14, v242, 2
	v_mov_b32_e32 v1, 0
	v_mbcnt_hi_u32_b32 v9, -1, v205
	v_lshl_or_b32 v7, s14, 7, v0
	v_lshlrev_b32_e32 v0, 11, v171
	v_lshl_add_u64 v[2:3], s[40:41], 0, v[0:1]
	v_lshlrev_b32_e32 v0, 1, v7
	v_and_b32_e32 v11, 64, v9
	v_lshl_add_u64 v[2:3], v[2:3], 0, v[0:1]
	v_lshl_add_u64 v[4:5], s[36:37], 0, v[0:1]
	v_or_b32_e32 v0, 32, v7
	v_or_b32_e32 v6, 64, v7
	v_or_b32_e32 v8, 0x60, v7
	v_add_u32_e32 v7, -1, v9
	v_cmp_lt_i32_e32 vcc, v7, v11
	s_and_b32 s8, s97, 0x3ffffc0
	s_lshl_b32 s8, s8, 6
	v_cndmask_b32_e32 v7, v7, v9, vcc
	v_lshlrev_b32_e32 v13, 2, v7
	v_add_u32_e32 v7, -2, v9
	v_cmp_lt_i32_e32 vcc, v7, v11
	v_lshl_or_b32 v19, v197, 8, s8
	s_lshl_b32 s8, s14, 3
	v_cndmask_b32_e32 v7, v7, v9, vcc
	v_lshlrev_b32_e32 v14, 2, v7
	v_add_u32_e32 v7, -4, v9
	v_cmp_lt_i32_e32 vcc, v7, v11
	s_lshl_b32 s22, s14, 1
	s_add_i32 s9, s8, 0
	v_cndmask_b32_e32 v7, v7, v9, vcc
	v_lshlrev_b32_e32 v15, 2, v7
	v_add_u32_e32 v7, -8, v9
	v_cmp_lt_i32_e32 vcc, v7, v11
	s_mov_b32 s23, 0
	v_lshl_add_u32 v10, v171, 2, 0
	v_cndmask_b32_e32 v7, v7, v9, vcc
	v_lshlrev_b32_e32 v16, 2, v7
	v_add_u32_e32 v7, -16, v9
	v_cmp_lt_i32_e32 vcc, v7, v11
	s_add_u32 s40, s50, s8
	s_addc_u32 s41, s51, 0
	v_cndmask_b32_e32 v7, v7, v9, vcc
	v_lshlrev_b32_e32 v17, 2, v7
	v_subrev_u32_e32 v7, 32, v9
	v_cmp_lt_i32_e32 vcc, v7, v11
	s_lshl_b64 s[58:59], s[22:23], 16
	s_or_b32 s22, s22, 1
	v_cndmask_b32_e32 v7, v7, v9, vcc
	v_add_u32_e32 v19, v10, v19
	v_cmp_eq_u32_e64 s[0:1], 63, v204
	v_lshl_add_u32 v12, v204, 6, s9
	v_cmp_eq_u32_e64 s[8:9], 0, v204
	v_cmp_gt_u32_e64 s[10:11], 2, v204
	v_cmp_gt_u32_e64 s[12:13], 4, v204
	v_cmp_gt_u32_e64 s[16:17], 8, v204
	v_cmp_gt_u32_e64 s[18:19], 16, v204
	v_lshlrev_b32_e32 v18, 2, v7
	v_cmp_gt_u32_e64 s[20:21], 32, v204
	s_lshl_b32 s14, s14, 9
	s_lshl_b64 s[62:63], s[22:23], 16
	s_lshl_b32 s56, s54, 6
	v_lshlrev_b32_e32 v0, 1, v0
	v_lshlrev_b32_e32 v6, 1, v6
	v_mov_b32_e32 v7, v1
	v_lshlrev_b32_e32 v8, 1, v8
	v_mov_b32_e32 v9, v1
	v_mov_b32_e32 v20, 0x358637bd
	s_mov_b32 s57, 0xf800000
	v_mov_b32_e32 v21, 0x260
	s_mov_b32 s64, 0xbfb8aa3b
	v_add_u32_e32 v22, 0x400, v19
	v_add_u32_e32 v23, 0x800, v19
	v_add_u32_e32 v24, 0xc00, v19
	s_and_b32 s65, s2, 7
	s_lshl_b32 s65, s65, 3
	s_bfe_u32 s15, s2, 0x30003
	s_add_i32 s65, s65, s15
	s_lshl_b32 s65, s65, 2
	s_lshr_b32 s15, s2, 6
	s_add_i32 s65, s65, s15
	s_lshl_b32 s15, s65, 6
	s_branch .LBB0_443
